# v55 + MLA attention steps: first K-fragment LDS read ahead of the LDS-DMA tile loads; wave-half mask by s_andn2 instead of cndmask+cmp
# speedup vs baseline: 1.0167x; 1.0008x over previous
.LBB0_422:
	s_setprio 3
	s_add_i32 s41, s58, 0xfffc0000
	s_mov_b32 s30, s28
	s_mov_b32 s28, s40
	v_add_u32_e32 v0, s30, v134
	ds_read_b128 v[34:37], v0
	s_add_i32 s40, s57, -1
	s_and_b32 s41, s41, 0xf00000
	s_and_b32 s55, s40, 3
	s_lshl_b32 s78, s41, 1
	s_add_i32 s53, s29, 0
	v_lshl_add_u64 v[238:239], v[128:129], 0, s[78:79]
	s_lshl_b32 s40, s55, 16
	s_mov_b32 s41, s79
	s_add_i32 s54, s53, s27
	v_lshl_add_u64 v[238:239], v[238:239], 0, s[40:41]
	s_mov_b32 m0, s54
	s_andn2_b64 s[40:41], exec, s[38:39]
	global_load_lds_dwordx4 v[238:239], off
	s_andn2_b64 vcc, exec, s[38:39]
	s_cbranch_vccnz .LBB0_424
	v_lshl_add_u64 v[238:239], v[124:125], 0, s[78:79]
	s_mul_i32 s60, s55, 0x38000
	s_mov_b32 s61, s79
	s_add_i32 s56, s53, s5
	v_lshl_add_u64 v[238:239], v[238:239], 0, s[60:61]
	s_add_i32 m0, s56, 0x2000
	s_nop 0
	global_load_lds_dwordx4 v[238:239], off
.LBB0_424:
	s_lshl_b32 s55, s55, 15
	v_lshl_add_u64 v[238:239], v[130:131], 0, s[78:79]
	s_lshl_b32 s78, s55, 1
	v_lshl_add_u64 v[238:239], v[238:239], 0, s[78:79]
	s_add_i32 s55, s54, 0x3000
	v_lshl_add_u64 v[238:239], v[238:239], 0, s[24:25]
	s_mov_b32 m0, s55
	s_nop 0
	global_load_lds_dwordx4 v[238:239], off
	s_add_i32 s56, s30, 0
	v_exp_f32_e32 v153, v66
	v_exp_f32_e32 v166, v67
	v_exp_f32_e32 v167, v68
	v_exp_f32_e32 v168, v69
	v_exp_f32_e32 v169, v70
	v_exp_f32_e32 v170, v71
	v_exp_f32_e32 v171, v72
	v_exp_f32_e32 v172, v73
	s_waitcnt lgkmcnt(0)
	v_mfma_f32_32x32x16_bf16 v[82:97], v[34:37], v[118:121], v[50:65]
	ds_read_b128 v[34:37], v0 offset:2048
	ds_read_b128 v[38:41], v0 offset:4096
	v_exp_f32_e32 v173, v74
	v_exp_f32_e32 v174, v75
	v_exp_f32_e32 v175, v76
	v_exp_f32_e32 v176, v77
	v_exp_f32_e32 v177, v78
	v_exp_f32_e32 v178, v79
	s_waitcnt lgkmcnt(0)
	v_mfma_f32_32x32x16_bf16 v[82:97], v[34:37], v[114:117], v[82:97]
	ds_read_b128 v[34:37], v0 offset:6144
	v_exp_f32_e32 v179, v80
	v_exp_f32_e32 v180, v81
	v_mfma_f32_32x32x16_bf16 v[82:97], v[38:41], v[110:113], v[82:97]
	ds_read_b128 v[38:41], v0 offset:8192
	s_waitcnt lgkmcnt(0)
	v_mfma_f32_32x32x16_bf16 v[82:97], v[34:37], v[106:109], v[82:97]
	v_add_f32_e32 v34, v141, v146
	v_add_f32_e32 v66, v138, v34
	ds_read_b128 v[34:37], v0 offset:10240
	s_setprio 2
	v_mfma_f32_32x32x16_bf16 v[82:97], v[38:41], v[102:105], v[82:97]
	ds_read_b128 v[38:41], v0 offset:512
	ds_read_b128 v[42:45], v0 offset:2560
	ds_read_b128 v[46:49], v0 offset:4608
	ds_read_b128 v[154:157], v0 offset:6656
	ds_read_b128 v[158:161], v0 offset:8704
	ds_read_b128 v[162:165], v0 offset:10752
	v_add_f32_e32 v0, v142, v66
	v_add_f32_e32 v0, v143, v0
	v_add_f32_e32 v0, v147, v0
	v_add_f32_e32 v0, v148, v0
	v_add_f32_e32 v0, v151, v0
	v_add_f32_e32 v0, v137, v0
	s_waitcnt lgkmcnt(0)
	v_mfma_f32_32x32x16_bf16 v[66:81], v[38:41], v[118:121], v[50:65]
	v_add_f32_e32 v0, v139, v0
	v_add_f32_e32 v0, v140, v0
	v_add_f32_e32 v0, v144, v0
	v_add_f32_e32 v0, v145, v0
	v_add_f32_e32 v0, v149, v0
	v_add_f32_e32 v0, v150, v0
	v_add_f32_e32 v0, v152, v0
	v_mfma_f32_32x32x16_bf16 v[66:81], v[42:45], v[114:117], v[66:81]
	v_add_f32_e32 v0, v153, v0
	v_add_f32_e32 v0, v166, v0
	v_add_f32_e32 v0, v167, v0
	v_add_f32_e32 v0, v168, v0
	v_add_f32_e32 v0, v169, v0
	v_add_f32_e32 v0, v170, v0
	v_add_f32_e32 v0, v171, v0
	v_mfma_f32_32x32x16_bf16 v[66:81], v[46:49], v[110:113], v[66:81]
	v_add_f32_e32 v0, v172, v0
	v_add_f32_e32 v0, v173, v0
	v_add_f32_e32 v0, v174, v0
	v_add_f32_e32 v0, v175, v0
	v_add_f32_e32 v0, v176, v0
	v_add_f32_e32 v0, v177, v0
	v_add_f32_e32 v0, v178, v0
	v_mfma_f32_32x32x16_bf16 v[66:81], v[154:157], v[106:109], v[66:81]
	v_add_f32_e32 v181, v179, v0
	v_cvt_pk_bf16_f32 v38, v137, v139
	v_cvt_pk_bf16_f32 v39, v140, v144
	v_cvt_pk_bf16_f32 v40, v145, v149
	v_cvt_pk_bf16_f32 v41, v150, v152
	v_cvt_pk_bf16_f32 v42, v153, v166
	v_cvt_pk_bf16_f32 v43, v167, v168
	v_mfma_f32_32x32x16_bf16 v[66:81], v[158:161], v[102:105], v[66:81]
	v_cvt_pk_bf16_f32 v44, v169, v170
	v_cvt_pk_bf16_f32 v45, v171, v172
	v_cvt_pk_bf16_f32 v46, v173, v174
	v_cvt_pk_bf16_f32 v47, v175, v176
	v_cvt_pk_bf16_f32 v48, v177, v178
	v_cvt_pk_bf16_f32 v49, v179, v180
	v_mfma_f32_32x32x16_bf16 v[82:97], v[34:37], v[98:101], v[82:97]
	v_cvt_pk_bf16_f32 v34, v141, v146
	v_cvt_pk_bf16_f32 v35, v138, v142
	v_cvt_pk_bf16_f32 v36, v143, v147
	v_cvt_pk_bf16_f32 v37, v148, v151
	v_mfma_f32_32x32x16_bf16 v[66:81], v[162:165], v[98:101], v[66:81]
	s_add_i32 s59, s28, 0
	v_add_u32_e32 v0, s59, v133
	ds_read_b64_tr_b16 v[138:139], v0 offset:12288
	ds_read_b64_tr_b16 v[140:141], v0 offset:12800
	ds_read_b64_tr_b16 v[142:143], v0 offset:16384
	s_nop 5
	v_max_f32_e32 v137, v67, v67
	s_waitcnt lgkmcnt(1)
	v_mfma_f32_32x32x16_bf16 v[18:33], v[138:141], v[34:37], v[18:33]
	ds_read_b64_tr_b16 v[144:145], v0 offset:16896
	ds_read_b64_tr_b16 v[138:139], v0 offset:13312
	s_waitcnt lgkmcnt(1)
	v_mfma_f32_32x32x16_bf16 v[2:17], v[142:145], v[34:37], v[2:17]
	ds_read_b64_tr_b16 v[140:141], v0 offset:13824
	ds_read_b64_tr_b16 v[34:35], v0 offset:17408
	s_setprio 1
	s_waitcnt lgkmcnt(1)
	v_mfma_f32_32x32x16_bf16 v[18:33], v[138:141], v[38:41], v[18:33]
	ds_read_b64_tr_b16 v[36:37], v0 offset:17920
	ds_read_b64_tr_b16 v[138:139], v0 offset:14336
	s_waitcnt lgkmcnt(1)
	v_mfma_f32_32x32x16_bf16 v[2:17], v[34:37], v[38:41], v[2:17]
	ds_read_b64_tr_b16 v[140:141], v0 offset:14848
	ds_read_b64_tr_b16 v[34:35], v0 offset:15360
	ds_read_b64_tr_b16 v[36:37], v0 offset:15872
	ds_read_b64_tr_b16 v[38:39], v0 offset:18432
	ds_read_b64_tr_b16 v[40:41], v0 offset:18944
	ds_read_b64_tr_b16 v[142:143], v0 offset:19456
	ds_read_b64_tr_b16 v[144:145], v0 offset:19968
	s_waitcnt lgkmcnt(6)
	v_mfma_f32_32x32x16_bf16 v[18:33], v[138:141], v[42:45], v[18:33]
	v_max_f32_e32 v138, v83, v83
	v_max_f32_e32 v137, v138, v137
	v_max3_f32 v138, v82, v66, v84
	v_max3_f32 v137, v137, v85, v69
	v_max3_f32 v138, v138, v68, v86
	v_max3_f32 v137, v137, v87, v71
	s_waitcnt lgkmcnt(2)
	v_mfma_f32_32x32x16_bf16 v[2:17], v[38:41], v[42:45], v[2:17]
	v_max3_f32 v38, v138, v70, v88
	v_max3_f32 v39, v137, v89, v73
	v_max3_f32 v38, v38, v72, v90
	v_max3_f32 v39, v39, v91, v75
	v_max3_f32 v38, v38, v74, v92
	v_max3_f32 v39, v39, v93, v77
	v_max3_f32 v38, v38, v76, v94
	v_mfma_f32_32x32x16_bf16 v[18:33], v[34:37], v[46:49], v[18:33]
	v_max3_f32 v34, v39, v95, v79
	v_max3_f32 v35, v38, v78, v96
	v_max3_f32 v34, v34, v97, v81
	v_add_f32_e32 v36, v180, v181
	v_max3_f32 v34, v35, v80, v34
	v_add_f32_e32 v136, v136, v36
	v_cmp_lt_f32_e32 vcc, s33, v34
	s_waitcnt lgkmcnt(0)
	v_mfma_f32_32x32x16_bf16 v[2:17], v[142:145], v[46:49], v[2:17]
	s_cbranch_vccz .LBB0_426
	v_mov_b32_e32 v35, v34
	s_nop 1
	v_permlane32_swap_b32 v34, v35
	s_nop 1
	s_nop 0
	v_max3_f32 v36, v34, v35, 0
	v_exp_f32_e64 v38, -v36
	v_add_f32_e32 v135, v135, v36
	v_xor_b32_e32 v34, 0x80000000, v135
	v_pk_add_f32 v[82:83], v[82:83], v[36:37] op_sel_hi:[1,0] neg_lo:[0,1] neg_hi:[0,1]
	v_pk_add_f32 v[84:85], v[84:85], v[36:37] op_sel_hi:[1,0] neg_lo:[0,1] neg_hi:[0,1]
	v_pk_add_f32 v[86:87], v[86:87], v[36:37] op_sel_hi:[1,0] neg_lo:[0,1] neg_hi:[0,1]
	v_pk_add_f32 v[88:89], v[88:89], v[36:37] op_sel_hi:[1,0] neg_lo:[0,1] neg_hi:[0,1]
	v_pk_add_f32 v[90:91], v[90:91], v[36:37] op_sel_hi:[1,0] neg_lo:[0,1] neg_hi:[0,1]
	v_pk_add_f32 v[92:93], v[92:93], v[36:37] op_sel_hi:[1,0] neg_lo:[0,1] neg_hi:[0,1]
	v_pk_add_f32 v[94:95], v[94:95], v[36:37] op_sel_hi:[1,0] neg_lo:[0,1] neg_hi:[0,1]
	v_pk_add_f32 v[96:97], v[96:97], v[36:37] op_sel_hi:[1,0] neg_lo:[0,1] neg_hi:[0,1]
	v_sub_f32_e32 v81, v81, v36
	v_sub_f32_e32 v80, v80, v36
	v_sub_f32_e32 v79, v79, v36
	v_sub_f32_e32 v78, v78, v36
	v_sub_f32_e32 v77, v77, v36
	v_sub_f32_e32 v76, v76, v36
	v_sub_f32_e32 v75, v75, v36
	v_sub_f32_e32 v74, v74, v36
	v_sub_f32_e32 v73, v73, v36
	v_sub_f32_e32 v72, v72, v36
	v_sub_f32_e32 v71, v71, v36
	v_sub_f32_e32 v70, v70, v36
	v_sub_f32_e32 v69, v69, v36
	v_sub_f32_e32 v68, v68, v36
	v_sub_f32_e32 v67, v67, v36
	v_sub_f32_e32 v66, v66, v36
	v_pk_mul_f32 v[32:33], v[32:33], v[38:39] op_sel_hi:[1,0]
	v_pk_mul_f32 v[30:31], v[30:31], v[38:39] op_sel_hi:[1,0]
	v_pk_mul_f32 v[28:29], v[28:29], v[38:39] op_sel_hi:[1,0]
	v_pk_mul_f32 v[26:27], v[26:27], v[38:39] op_sel_hi:[1,0]
	v_pk_mul_f32 v[24:25], v[24:25], v[38:39] op_sel_hi:[1,0]
	v_pk_mul_f32 v[22:23], v[22:23], v[38:39] op_sel_hi:[1,0]
	v_pk_mul_f32 v[20:21], v[20:21], v[38:39] op_sel_hi:[1,0]
	v_pk_mul_f32 v[18:19], v[18:19], v[38:39] op_sel_hi:[1,0]
	v_pk_mul_f32 v[16:17], v[16:17], v[38:39] op_sel_hi:[1,0]
	v_pk_mul_f32 v[14:15], v[14:15], v[38:39] op_sel_hi:[1,0]
	v_pk_mul_f32 v[12:13], v[12:13], v[38:39] op_sel_hi:[1,0]
	v_pk_mul_f32 v[10:11], v[10:11], v[38:39] op_sel_hi:[1,0]
	v_pk_mul_f32 v[8:9], v[8:9], v[38:39] op_sel_hi:[1,0]
	v_pk_mul_f32 v[6:7], v[6:7], v[38:39] op_sel_hi:[1,0]
	v_pk_mul_f32 v[4:5], v[4:5], v[38:39] op_sel_hi:[1,0]
	v_pk_mul_f32 v[2:3], v[2:3], v[38:39] op_sel_hi:[1,0]
	v_mul_f32_e32 v136, v136, v38
	v_mov_b32_e32 v35, v34
	v_mov_b32_e32 v36, v34
	v_mov_b32_e32 v37, v34
	v_mov_b32_e32 v38, v34
	v_mov_b32_e32 v39, v34
	v_mov_b32_e32 v40, v34
	v_mov_b32_e32 v41, v34
	v_mov_b32_e32 v42, v34
	v_mov_b32_e32 v43, v34
	v_mov_b32_e32 v44, v34
	v_mov_b32_e32 v45, v34
	v_mov_b32_e32 v46, v34
	v_mov_b32_e32 v47, v34
	v_mov_b32_e32 v48, v34
	v_mov_b32_e32 v49, v34
	v_mov_b32_e32 v50, v34
	v_mov_b32_e32 v51, v34
	v_mov_b32_e32 v52, v34
	v_mov_b32_e32 v53, v34
	v_mov_b32_e32 v54, v34
	v_mov_b32_e32 v55, v34
	v_mov_b32_e32 v56, v34
	v_mov_b32_e32 v57, v34
	v_mov_b32_e32 v58, v34
	v_mov_b32_e32 v59, v34
	v_mov_b32_e32 v60, v34
	v_mov_b32_e32 v61, v34
	v_mov_b32_e32 v62, v34
	v_mov_b32_e32 v63, v34
	v_mov_b32_e32 v64, v34
	v_mov_b32_e32 v65, v34
	s_branch .LBB0_427
.LBB0_426:
.LBB0_427:
	s_setprio 0
	s_add_i32 s60, s57, 4
	s_and_b32 s61, s58, 0xf00000
	s_and_b32 s60, s60, 3
	s_lshl_b32 s78, s61, 1
	v_lshl_add_u64 v[238:239], v[128:129], 0, s[78:79]
	s_lshl_b32 s62, s60, 16
	s_mov_b32 s63, s79
	s_add_i32 s61, s59, s27
	v_lshl_add_u64 v[238:239], v[238:239], 0, s[62:63]
	s_mov_b32 m0, s61
	s_waitcnt vmcnt(0)
	s_barrier
	s_setprio 3
	v_add_u32_e32 v158, s53, v134
	ds_read_b128 v[138:141], v158
	global_load_lds_dwordx4 v[238:239], off
	s_and_b64 vcc, exec, s[40:41]
	s_cbranch_vccnz .LBB0_429
	v_lshl_add_u64 v[238:239], v[124:125], 0, s[78:79]
	s_mul_i32 s40, s60, 0x38000
	s_mov_b32 s41, s79
	v_lshl_add_u64 v[238:239], v[238:239], 0, s[40:41]
	s_add_i32 s40, s59, s5
	s_add_i32 m0, s40, 0x2000
	s_nop 0
	global_load_lds_dwordx4 v[238:239], off
.LBB0_429:
	s_lshl_b32 s40, s60, 15
	v_exp_f32_e32 v137, v82
	v_exp_f32_e32 v162, v83
	v_lshl_add_u64 v[82:83], v[130:131], 0, s[78:79]
	s_lshl_b32 s78, s40, 1
	v_lshl_add_u64 v[82:83], v[82:83], 0, s[78:79]
	v_lshl_add_u64 v[82:83], v[82:83], 0, s[24:25]
	s_add_i32 m0, s61, 0x3000
	v_exp_f32_e32 v163, v84
	global_load_lds_dwordx4 v[82:83], off
	v_exp_f32_e32 v164, v85
	v_exp_f32_e32 v165, v86
	v_exp_f32_e32 v166, v87
	v_exp_f32_e32 v167, v88
	v_exp_f32_e32 v168, v89
	v_exp_f32_e32 v169, v90
	v_exp_f32_e32 v170, v91
	v_exp_f32_e32 v171, v92
	v_exp_f32_e32 v172, v93
	v_exp_f32_e32 v173, v94
	v_exp_f32_e32 v174, v95
	v_exp_f32_e32 v175, v96
	v_exp_f32_e32 v176, v97
	v_exp_f32_e32 v177, v66
	v_exp_f32_e32 v178, v67
	v_exp_f32_e32 v179, v68
	v_exp_f32_e32 v180, v69
	v_exp_f32_e32 v181, v70
	v_exp_f32_e32 v182, v71
	v_exp_f32_e32 v183, v72
	v_exp_f32_e32 v184, v73
	s_waitcnt lgkmcnt(0)
	v_mfma_f32_32x32x16_bf16 v[82:97], v[138:141], v[118:121], v[50:65]
	ds_read_b128 v[138:141], v158 offset:2048
	ds_read_b128 v[142:145], v158 offset:4096
	ds_read_b128 v[66:69], v158 offset:6144
	ds_read_b128 v[70:73], v158 offset:8192
	v_exp_f32_e32 v185, v74
	v_add_f32_e32 v74, v137, v162
	v_exp_f32_e32 v186, v75
	v_exp_f32_e32 v187, v76
	s_waitcnt lgkmcnt(0)
	v_mfma_f32_32x32x16_bf16 v[82:97], v[138:141], v[114:117], v[82:97]
	v_exp_f32_e32 v188, v77
	v_exp_f32_e32 v189, v78
	v_exp_f32_e32 v199, v79
	v_exp_f32_e32 v200, v80
	v_exp_f32_e32 v201, v81
	v_mfma_f32_32x32x16_bf16 v[82:97], v[142:145], v[110:113], v[82:97]
	v_mfma_f32_32x32x16_bf16 v[82:97], v[66:69], v[106:109], v[82:97]
	ds_read_b128 v[138:141], v158 offset:512
	ds_read_b128 v[66:69], v158 offset:10240
	ds_read_b128 v[142:145], v158 offset:2560
	ds_read_b128 v[146:149], v158 offset:4608
	ds_read_b128 v[150:153], v158 offset:6656
	ds_read_b128 v[154:157], v158 offset:8704
	s_setprio 2
	ds_read_b128 v[158:161], v158 offset:10752
	v_mfma_f32_32x32x16_bf16 v[82:97], v[70:73], v[102:105], v[82:97]
	v_add_f32_e32 v70, v163, v74
	v_add_f32_e32 v70, v164, v70
	s_waitcnt lgkmcnt(0)
	v_mfma_f32_32x32x16_bf16 v[82:97], v[66:69], v[98:101], v[82:97]
	v_add_f32_e32 v66, v165, v70
	v_add_f32_e32 v66, v166, v66
	v_add_f32_e32 v66, v167, v66
	v_add_f32_e32 v66, v168, v66
	v_add_f32_e32 v66, v169, v66
	v_add_f32_e32 v66, v170, v66
	v_add_f32_e32 v202, v171, v66
	v_mfma_f32_32x32x16_bf16 v[66:81], v[138:141], v[118:121], v[50:65]
	v_add_f32_e32 v138, v172, v202
	v_add_f32_e32 v138, v173, v138
	v_add_f32_e32 v138, v174, v138
	v_add_f32_e32 v138, v175, v138
	v_add_f32_e32 v138, v176, v138
	v_add_f32_e32 v138, v177, v138
	v_add_f32_e32 v138, v178, v138
	v_mfma_f32_32x32x16_bf16 v[66:81], v[142:145], v[114:117], v[66:81]
	v_add_f32_e32 v138, v179, v138
	v_add_f32_e32 v138, v180, v138
	v_add_f32_e32 v138, v181, v138
	v_add_f32_e32 v138, v182, v138
	v_add_f32_e32 v138, v183, v138
	v_add_f32_e32 v138, v184, v138
	v_add_f32_e32 v138, v185, v138
	v_mfma_f32_32x32x16_bf16 v[66:81], v[146:149], v[110:113], v[66:81]
	v_add_f32_e32 v138, v186, v138
	v_add_f32_e32 v138, v187, v138
	v_add_f32_e32 v138, v188, v138
	v_add_f32_e32 v138, v189, v138
	v_add_f32_e32 v138, v199, v138
	v_add_f32_e32 v202, v200, v138
	v_cvt_pk_bf16_f32 v138, v137, v162
	v_mfma_f32_32x32x16_bf16 v[66:81], v[150:153], v[106:109], v[66:81]
	v_cvt_pk_bf16_f32 v139, v163, v164
	v_cvt_pk_bf16_f32 v140, v165, v166
	v_cvt_pk_bf16_f32 v141, v167, v168
	v_cvt_pk_bf16_f32 v142, v169, v170
	v_cvt_pk_bf16_f32 v143, v171, v172
	v_cvt_pk_bf16_f32 v144, v173, v174
	v_cvt_pk_bf16_f32 v145, v175, v176
	v_mfma_f32_32x32x16_bf16 v[66:81], v[154:157], v[102:105], v[66:81]
	v_cvt_pk_bf16_f32 v146, v177, v178
	v_cvt_pk_bf16_f32 v147, v179, v180
	v_cvt_pk_bf16_f32 v148, v181, v182
	v_cvt_pk_bf16_f32 v149, v183, v184
	v_cvt_pk_bf16_f32 v150, v185, v186
	v_cvt_pk_bf16_f32 v151, v187, v188
	v_cvt_pk_bf16_f32 v152, v189, v199
	v_mfma_f32_32x32x16_bf16 v[66:81], v[158:161], v[98:101], v[66:81]
	v_cvt_pk_bf16_f32 v153, v200, v201
	v_add_u32_e32 v137, s56, v133
	ds_read_b64_tr_b16 v[154:155], v137 offset:12288
	ds_read_b64_tr_b16 v[156:157], v137 offset:12800
	ds_read_b64_tr_b16 v[158:159], v137 offset:16384
	s_waitcnt lgkmcnt(1)
	v_mfma_f32_32x32x16_bf16 v[18:33], v[154:157], v[138:141], v[18:33]
	ds_read_b64_tr_b16 v[160:161], v137 offset:16896
	ds_read_b64_tr_b16 v[154:155], v137 offset:13312
	s_waitcnt lgkmcnt(1)
	v_mfma_f32_32x32x16_bf16 v[2:17], v[158:161], v[138:141], v[2:17]
	ds_read_b64_tr_b16 v[156:157], v137 offset:13824
	ds_read_b64_tr_b16 v[138:139], v137 offset:17408
	s_waitcnt lgkmcnt(1)
	v_mfma_f32_32x32x16_bf16 v[18:33], v[154:157], v[142:145], v[18:33]
	ds_read_b64_tr_b16 v[140:141], v137 offset:17920
	ds_read_b64_tr_b16 v[154:155], v137 offset:14336
	s_waitcnt lgkmcnt(1)
	s_setprio 1
	v_mfma_f32_32x32x16_bf16 v[2:17], v[138:141], v[142:145], v[2:17]
	ds_read_b64_tr_b16 v[156:157], v137 offset:14848
	ds_read_b64_tr_b16 v[138:139], v137 offset:15360
	ds_read_b64_tr_b16 v[140:141], v137 offset:15872
	ds_read_b64_tr_b16 v[142:143], v137 offset:18432
	ds_read_b64_tr_b16 v[144:145], v137 offset:18944
	ds_read_b64_tr_b16 v[158:159], v137 offset:19456
	ds_read_b64_tr_b16 v[160:161], v137 offset:19968
	v_max_f32_e32 v137, v67, v67
	s_waitcnt lgkmcnt(6)
	v_mfma_f32_32x32x16_bf16 v[18:33], v[154:157], v[146:149], v[18:33]
	v_max_f32_e32 v154, v83, v83
	v_max_f32_e32 v137, v154, v137
	v_max3_f32 v154, v82, v66, v84
	v_max3_f32 v137, v137, v85, v69
	v_max3_f32 v154, v154, v68, v86
	v_max3_f32 v137, v137, v87, v71
	v_max3_f32 v137, v137, v89, v73
	s_waitcnt lgkmcnt(2)
	v_mfma_f32_32x32x16_bf16 v[2:17], v[142:145], v[146:149], v[2:17]
	v_max3_f32 v142, v154, v70, v88
	v_max3_f32 v142, v142, v72, v90
	v_max3_f32 v137, v137, v91, v75
	v_max3_f32 v142, v142, v74, v92
	v_max3_f32 v137, v137, v93, v77
	v_max3_f32 v142, v142, v76, v94
	v_max3_f32 v137, v137, v95, v79
	v_mfma_f32_32x32x16_bf16 v[18:33], v[138:141], v[150:153], v[18:33]
	v_max3_f32 v138, v142, v78, v96
	v_max3_f32 v137, v137, v97, v81
	v_add_f32_e32 v139, v201, v202
	v_max3_f32 v137, v138, v80, v137
	v_add_f32_e32 v136, v136, v139
	v_cmp_lt_f32_e32 vcc, s33, v137
	s_waitcnt lgkmcnt(0)
	v_mfma_f32_32x32x16_bf16 v[2:17], v[158:161], v[150:153], v[2:17]
	s_cbranch_vccz .LBB0_431
	v_mov_b32_e32 v34, v137
	s_nop 1
	v_permlane32_swap_b32 v137, v34
	s_nop 1
	s_nop 0
	v_max3_f32 v36, v137, v34, 0
	v_exp_f32_e64 v38, -v36
	v_add_f32_e32 v135, v135, v36
	v_xor_b32_e32 v34, 0x80000000, v135
	v_pk_add_f32 v[82:83], v[82:83], v[36:37] op_sel_hi:[1,0] neg_lo:[0,1] neg_hi:[0,1]
	v_pk_add_f32 v[84:85], v[84:85], v[36:37] op_sel_hi:[1,0] neg_lo:[0,1] neg_hi:[0,1]
	v_pk_add_f32 v[86:87], v[86:87], v[36:37] op_sel_hi:[1,0] neg_lo:[0,1] neg_hi:[0,1]
	v_pk_add_f32 v[88:89], v[88:89], v[36:37] op_sel_hi:[1,0] neg_lo:[0,1] neg_hi:[0,1]
	v_pk_add_f32 v[90:91], v[90:91], v[36:37] op_sel_hi:[1,0] neg_lo:[0,1] neg_hi:[0,1]
	v_pk_add_f32 v[92:93], v[92:93], v[36:37] op_sel_hi:[1,0] neg_lo:[0,1] neg_hi:[0,1]
	v_pk_add_f32 v[94:95], v[94:95], v[36:37] op_sel_hi:[1,0] neg_lo:[0,1] neg_hi:[0,1]
	v_pk_add_f32 v[96:97], v[96:97], v[36:37] op_sel_hi:[1,0] neg_lo:[0,1] neg_hi:[0,1]
	v_sub_f32_e32 v81, v81, v36
	v_sub_f32_e32 v80, v80, v36
	v_sub_f32_e32 v79, v79, v36
	v_sub_f32_e32 v78, v78, v36
	v_sub_f32_e32 v77, v77, v36
	v_sub_f32_e32 v76, v76, v36
	v_sub_f32_e32 v75, v75, v36
	v_sub_f32_e32 v74, v74, v36
	v_sub_f32_e32 v73, v73, v36
	v_sub_f32_e32 v72, v72, v36
	v_sub_f32_e32 v71, v71, v36
	v_sub_f32_e32 v70, v70, v36
	v_sub_f32_e32 v69, v69, v36
	v_sub_f32_e32 v68, v68, v36
	v_sub_f32_e32 v67, v67, v36
	v_sub_f32_e32 v66, v66, v36
	v_pk_mul_f32 v[32:33], v[32:33], v[38:39] op_sel_hi:[1,0]
	v_pk_mul_f32 v[30:31], v[30:31], v[38:39] op_sel_hi:[1,0]
	v_pk_mul_f32 v[28:29], v[28:29], v[38:39] op_sel_hi:[1,0]
	v_pk_mul_f32 v[26:27], v[26:27], v[38:39] op_sel_hi:[1,0]
	v_pk_mul_f32 v[24:25], v[24:25], v[38:39] op_sel_hi:[1,0]
	v_pk_mul_f32 v[22:23], v[22:23], v[38:39] op_sel_hi:[1,0]
	v_pk_mul_f32 v[20:21], v[20:21], v[38:39] op_sel_hi:[1,0]
	v_pk_mul_f32 v[18:19], v[18:19], v[38:39] op_sel_hi:[1,0]
	v_pk_mul_f32 v[16:17], v[16:17], v[38:39] op_sel_hi:[1,0]
	v_pk_mul_f32 v[14:15], v[14:15], v[38:39] op_sel_hi:[1,0]
	v_pk_mul_f32 v[12:13], v[12:13], v[38:39] op_sel_hi:[1,0]
	v_pk_mul_f32 v[10:11], v[10:11], v[38:39] op_sel_hi:[1,0]
	v_pk_mul_f32 v[8:9], v[8:9], v[38:39] op_sel_hi:[1,0]
	v_pk_mul_f32 v[6:7], v[6:7], v[38:39] op_sel_hi:[1,0]
	v_pk_mul_f32 v[4:5], v[4:5], v[38:39] op_sel_hi:[1,0]
	v_pk_mul_f32 v[2:3], v[2:3], v[38:39] op_sel_hi:[1,0]
	v_mul_f32_e32 v136, v136, v38
	v_mov_b32_e32 v35, v34
	v_mov_b32_e32 v36, v34
	v_mov_b32_e32 v37, v34
	v_mov_b32_e32 v38, v34
	v_mov_b32_e32 v39, v34
	v_mov_b32_e32 v40, v34
	v_mov_b32_e32 v41, v34
	v_mov_b32_e32 v42, v34
	v_mov_b32_e32 v43, v34
	v_mov_b32_e32 v44, v34
	v_mov_b32_e32 v45, v34
	v_mov_b32_e32 v46, v34
	v_mov_b32_e32 v47, v34
	v_mov_b32_e32 v48, v34
	v_mov_b32_e32 v49, v34
	v_mov_b32_e32 v50, v34
	v_mov_b32_e32 v51, v34
	v_mov_b32_e32 v52, v34
	v_mov_b32_e32 v53, v34
	v_mov_b32_e32 v54, v34
	v_mov_b32_e32 v55, v34
	v_mov_b32_e32 v56, v34
	v_mov_b32_e32 v57, v34
	v_mov_b32_e32 v58, v34
	v_mov_b32_e32 v59, v34
	v_mov_b32_e32 v60, v34
	v_mov_b32_e32 v61, v34
	v_mov_b32_e32 v62, v34
	v_mov_b32_e32 v63, v34
	v_mov_b32_e32 v64, v34
	v_mov_b32_e32 v65, v34
